# attention entry stagger with 4 groups (0/3.5/7/10.5us)
# baseline (speedup 1.0000x reference)
; DI void phase_attn1(const Params& p, char* smem) {
;   const int G = gridDim.x;
;   for (int round = 0; round * G < 512; ++round) {
;     const int j = (round & 1) ? (G - 1 - (int)blockIdx.x) : (int)blockIdx.x;
;     const int t = round * G + j;
;     if (t >= 512) continue;
;     const int qt = 15 - (t >> 5), bh = t & 31;
;     mla_item(p, bh >> 3, bh & 7, qt, smem);
;   }
.LBB0_1361:
	s_or_b64 exec, exec, s[0:1]
	s_not_b32 s0, s84
	s_add_i32 s27, s96, s0
	s_add_u32 s24, s22, 0x154c0000
	s_addc_u32 s25, s23, 0
	s_add_u32 s33, s22, 0x184c0000
	s_addc_u32 s40, s23, 0
	s_add_u32 s41, s22, 0x1a4c0000
	s_addc_u32 s44, s23, 0
	s_add_u32 s45, s22, 0x1a6c0000
	s_addc_u32 s46, s23, 0
	s_add_u32 s28, s22, 0x40c0000
	s_movk_i32 s34, 0xff00
	s_addc_u32 s29, s23, 0
	s_mov_b32 s31, 0
	s_movk_i32 s47, 0xc00
	v_mov_b32_e32 v0, 0
	s_mov_b32 s48, 0x2aaaaaab
	s_mov_b32 s35, -1
	s_movk_i32 s49, 0x190
	s_movk_i32 s50, 0x88
	s_movk_i32 s51, 0x6400
	s_mov_b32 s52, 0xf149f2ca
	s_mov_b32 s53, 0x3dd53b94
	s_mov_b32 s54, 0x41000000
	s_mov_b64 s[36:37], 0x20000
	s_mov_b64 s[38:39], 0x2000
	s_movk_i32 s55, 0x3300
	s_mov_b64 s[42:43], 0x80c0a00
	s_mov_b32 s56, 0x80c0000
	v_mov_b32_e32 v199, 0xf149f2ca
	v_mbcnt_hi_u32_b32 v198, -1, v207
	s_mov_b32 s0, 0
	s_mov_b32 s57, 0
	s_bitcmp1_b32 s84, 3
	s_cbranch_scc0 .Lstag_10a
	s_sleep 127
.Lstag_10a:
	s_bitcmp1_b32 s84, 4
	s_cbranch_scc0 .Lstag_10b
	s_sleep 127
	s_sleep 127
.Lstag_10b:
	s_waitcnt lgkmcnt(0)
	s_barrier
	s_branch .LBB0_1365
